# EpiK: the 8 row groups' statistics loads issued together at the first group (store-data WAR pad before the copies)
# baseline (speedup 1.0000x reference)
.LBB0_869:
	s_lshl_b32 s4, s76, 8
	v_mbcnt_lo_u32_b32 v136, -1, 0
	v_mbcnt_hi_u32_b32 v136, -1, v136
	s_add_i32 s4, s4, s34
	v_and_b32_e32 v155, 15, v136
	v_or_b32_e32 v144, s4, v155
	v_ashrrev_i32_e32 v145, 31, v144
	v_lshl_add_u64 v[142:143], v[144:145], 4, s[44:45]
	v_mov_b64_e32 v[250:251], v[142:143]
	global_load_dwordx4 v[182:185], v[250:251], off offset:256
	global_load_dwordx4 v[186:189], v[250:251], off offset:512
	global_load_dwordx4 v[190:193], v[250:251], off offset:768
	global_load_dwordx4 v[194:197], v[250:251], off offset:2048
	global_load_dwordx4 v[198:201], v[250:251], off offset:2304
	global_load_dwordx4 v[202:205], v[250:251], off offset:2560
	global_load_dwordx4 v[206:209], v[250:251], off offset:2816
	global_load_dwordx4 v[158:161], v[142:143], off
	v_ashrrev_i32_e32 v136, 1, v136
	v_and_b32_e32 v136, -8, v136
	v_add_u32_e32 v136, s35, v136
	v_mov_b32_e32 v145, s4
	v_lshl_add_u32 v148, s69, 8, v136
	s_ashr_i32 s5, s4, 9
	v_bitop3_b32 v157, v155, s43, v145 bitop3:0xc8
	v_or_b32_e32 v146, 16, v144
	v_ashrrev_i32_e32 v145, 6, v148
	v_add_u32_e32 v148, 0x80, v148
	s_and_b32 s5, s5, -8
	v_ashrrev_i32_e32 v147, 31, v146
	v_ashrrev_i32_e32 v156, 6, v148
	v_lshl_add_u64 v[162:163], v[146:147], 4, s[44:45]
	v_add_u32_e32 v146, s5, v145
	v_add_u32_e32 v164, s5, v156
	v_ashrrev_i32_e32 v147, 31, v146
	v_ashrrev_i32_e32 v165, 31, v164
	v_lshlrev_b64 v[148:149], 12, v[146:147]
	v_lshlrev_b64 v[146:147], 12, v[164:165]
	v_mov_b64_e32 v[142:143], s[22:23]
	v_or_b32_e32 v166, v148, v157
	v_or_b32_e32 v157, v146, v157
	v_mad_u64_u32 v[164:165], s[14:15], v166, s31, v[142:143]
	v_mad_u64_u32 v[166:167], s[14:15], v157, s31, v[142:143]
	v_and_b32_e32 v136, 56, v136
	v_lshlrev_b32_e32 v136, 1, v136
	v_mad_i32_i24 v165, v149, s31, v165
	v_mad_i32_i24 v167, v147, s31, v167
	s_waitcnt vmcnt(0)
	v_mov_b32_e32 v168, v159
	v_mov_b32_e32 v169, v160
	v_mov_b32_e32 v159, v161
	v_pk_add_f32 v[158:159], v[168:169], v[158:159]
	v_lshl_add_u64 v[160:161], v[166:167], 0, v[136:137]
	v_add_f32_e32 v157, v158, v159
	v_fmamk_f32 v157, v157, 0x3c000000, v154
	v_mul_f32_e32 v158, 0x4b800000, v157
	v_cmp_gt_f32_e32 vcc, s41, v157
	s_nop 1
	v_cndmask_b32_e32 v157, v157, v158, vcc
	v_rsq_f32_e32 v157, v157
	v_lshl_add_u64 v[158:159], v[164:165], 0, v[136:137]
	v_mul_f32_e32 v164, 0x45800000, v157
	v_cndmask_b32_e32 v164, v157, v164, vcc
	v_pk_mul_f32 v[114:115], v[114:115], v[164:165] op_sel_hi:[1,0]
	v_pk_mul_f32 v[112:113], v[112:113], v[164:165] op_sel_hi:[1,0]
	v_pk_mul_f32 v[118:119], v[118:119], v[164:165] op_sel_hi:[1,0]
	v_pk_mul_f32 v[116:117], v[116:117], v[164:165] op_sel_hi:[1,0]
	v_cvt_pk_bf16_f32 v112, v112, v113
	v_cvt_pk_bf16_f32 v113, v114, v115
	v_pk_mul_f32 v[122:123], v[122:123], v[164:165] op_sel_hi:[1,0]
	v_cvt_pk_bf16_f32 v114, v116, v117
	v_cvt_pk_bf16_f32 v115, v118, v119
	v_pk_mul_f32 v[120:121], v[120:121], v[164:165] op_sel_hi:[1,0]
	v_pk_mul_f32 v[126:127], v[126:127], v[164:165] op_sel_hi:[1,0]
	v_pk_mul_f32 v[124:125], v[124:125], v[164:165] op_sel_hi:[1,0]
	global_store_dwordx4 v[158:159], v[112:115], off
	v_or_b32_e32 v116, 32, v144
	v_ashrrev_i32_e32 v117, 31, v116
	v_cvt_pk_bf16_f32 v112, v120, v121
	v_cvt_pk_bf16_f32 v113, v122, v123
	v_cvt_pk_bf16_f32 v114, v124, v125
	v_cvt_pk_bf16_f32 v115, v126, v127
	global_store_dwordx4 v[160:161], v[112:115], off
	s_nop 1
	v_mov_b64_e32 v[112:113], v[182:183]
	v_mov_b64_e32 v[114:115], v[184:185]
	v_bitop3_b32 v120, v144, s8, 16 bitop3:0xc8
	v_or_b32_e32 v118, v148, v120
	v_mad_u64_u32 v[118:119], s[14:15], v118, s31, v[142:143]
	v_mad_i32_i24 v119, v149, s31, v119
	v_or_b32_e32 v120, v146, v120
	v_mad_u64_u32 v[120:121], s[14:15], v120, s31, v[142:143]
	v_mad_i32_i24 v121, v147, s31, v121
	v_lshl_add_u64 v[116:117], v[116:117], 4, s[44:45]
	v_mov_b32_e32 v122, v113
	v_mov_b32_e32 v123, v114
	v_mov_b32_e32 v113, v115
	v_pk_add_f32 v[112:113], v[122:123], v[112:113]
	v_lshl_add_u64 v[114:115], v[120:121], 0, v[136:137]
	v_add_f32_e32 v112, v112, v113
	v_fmamk_f32 v112, v112, 0x3c000000, v154
	v_mul_f32_e32 v113, 0x4b800000, v112
	v_cmp_gt_f32_e32 vcc, s41, v112
	s_nop 1
	v_cndmask_b32_e32 v112, v112, v113, vcc
	v_rsq_f32_e32 v122, v112
	v_lshl_add_u64 v[112:113], v[118:119], 0, v[136:137]
	v_mul_f32_e32 v118, 0x45800000, v122
	v_cndmask_b32_e32 v118, v122, v118, vcc
	v_pk_mul_f32 v[98:99], v[98:99], v[118:119] op_sel_hi:[1,0]
	v_pk_mul_f32 v[96:97], v[96:97], v[118:119] op_sel_hi:[1,0]
	v_pk_mul_f32 v[102:103], v[102:103], v[118:119] op_sel_hi:[1,0]
	v_pk_mul_f32 v[100:101], v[100:101], v[118:119] op_sel_hi:[1,0]
	v_cvt_pk_bf16_f32 v96, v96, v97
	v_cvt_pk_bf16_f32 v97, v98, v99
	v_pk_mul_f32 v[106:107], v[106:107], v[118:119] op_sel_hi:[1,0]
	v_cvt_pk_bf16_f32 v98, v100, v101
	v_cvt_pk_bf16_f32 v99, v102, v103
	v_pk_mul_f32 v[104:105], v[104:105], v[118:119] op_sel_hi:[1,0]
	v_pk_mul_f32 v[110:111], v[110:111], v[118:119] op_sel_hi:[1,0]
	v_pk_mul_f32 v[108:109], v[108:109], v[118:119] op_sel_hi:[1,0]
	global_store_dwordx4 v[112:113], v[96:99], off
	v_or_b32_e32 v100, 48, v144
	v_ashrrev_i32_e32 v101, 31, v100
	v_cvt_pk_bf16_f32 v96, v104, v105
	v_cvt_pk_bf16_f32 v97, v106, v107
	v_cvt_pk_bf16_f32 v98, v108, v109
	v_cvt_pk_bf16_f32 v99, v110, v111
	global_store_dwordx4 v[114:115], v[96:99], off
	s_nop 1
	v_mov_b64_e32 v[96:97], v[186:187]
	v_mov_b64_e32 v[98:99], v[188:189]
	v_bitop3_b32 v104, v144, s9, 32 bitop3:0xc8
	v_or_b32_e32 v102, v148, v104
	v_mad_u64_u32 v[102:103], s[14:15], v102, s31, v[142:143]
	v_mad_i32_i24 v103, v149, s31, v103
	v_or_b32_e32 v104, v146, v104
	v_mad_u64_u32 v[104:105], s[14:15], v104, s31, v[142:143]
	v_mad_i32_i24 v105, v147, s31, v105
	v_lshl_add_u64 v[100:101], v[100:101], 4, s[44:45]
	s_add_i32 s14, s4, 0x80
	v_mov_b32_e32 v106, v97
	v_mov_b32_e32 v107, v98
	v_mov_b32_e32 v97, v99
	v_pk_add_f32 v[96:97], v[106:107], v[96:97]
	v_lshl_add_u64 v[98:99], v[104:105], 0, v[136:137]
	v_add_f32_e32 v96, v96, v97
	v_fmamk_f32 v96, v96, 0x3c000000, v154
	v_mul_f32_e32 v97, 0x4b800000, v96
	v_cmp_gt_f32_e32 vcc, s41, v96
	s_nop 1
	v_cndmask_b32_e32 v96, v96, v97, vcc
	v_rsq_f32_e32 v106, v96
	v_lshl_add_u64 v[96:97], v[102:103], 0, v[136:137]
	v_mul_f32_e32 v102, 0x45800000, v106
	v_cndmask_b32_e32 v102, v106, v102, vcc
	v_pk_mul_f32 v[82:83], v[82:83], v[102:103] op_sel_hi:[1,0]
	v_pk_mul_f32 v[80:81], v[80:81], v[102:103] op_sel_hi:[1,0]
	v_pk_mul_f32 v[86:87], v[86:87], v[102:103] op_sel_hi:[1,0]
	v_pk_mul_f32 v[84:85], v[84:85], v[102:103] op_sel_hi:[1,0]
	v_cvt_pk_bf16_f32 v80, v80, v81
	v_cvt_pk_bf16_f32 v81, v82, v83
	v_pk_mul_f32 v[90:91], v[90:91], v[102:103] op_sel_hi:[1,0]
	v_cvt_pk_bf16_f32 v82, v84, v85
	v_cvt_pk_bf16_f32 v83, v86, v87
	v_pk_mul_f32 v[88:89], v[88:89], v[102:103] op_sel_hi:[1,0]
	v_pk_mul_f32 v[94:95], v[94:95], v[102:103] op_sel_hi:[1,0]
	v_pk_mul_f32 v[92:93], v[92:93], v[102:103] op_sel_hi:[1,0]
	global_store_dwordx4 v[96:97], v[80:83], off
	s_nop 1
	v_cvt_pk_bf16_f32 v80, v88, v89
	v_cvt_pk_bf16_f32 v81, v90, v91
	v_cvt_pk_bf16_f32 v82, v92, v93
	v_cvt_pk_bf16_f32 v83, v94, v95
	global_store_dwordx4 v[98:99], v[80:83], off
	s_nop 1
	v_mov_b64_e32 v[82:83], v[190:191]
	v_mov_b64_e32 v[84:85], v[192:193]
	v_bitop3_b32 v90, v144, s53, 48 bitop3:0xc8
	v_or_b32_e32 v80, s14, v155
	v_ashrrev_i32_e32 v81, 31, v80
	v_lshl_add_u64 v[86:87], v[80:81], 4, s[44:45]
	v_or_b32_e32 v81, v148, v90
	v_mad_u64_u32 v[88:89], s[4:5], v81, s31, v[142:143]
	v_or_b32_e32 v81, v146, v90
	v_mad_u64_u32 v[90:91], s[4:5], v81, s31, v[142:143]
	v_mad_i32_i24 v89, v149, s31, v89
	v_mad_i32_i24 v91, v147, s31, v91
	s_ashr_i32 s4, s14, 9
	s_and_b32 s4, s4, -8
	v_mov_b32_e32 v92, v83
	v_mov_b32_e32 v93, v84
	v_mov_b32_e32 v83, v85
	v_pk_add_f32 v[82:83], v[92:93], v[82:83]
	v_lshl_add_u64 v[84:85], v[90:91], 0, v[136:137]
	v_add_f32_e32 v81, v82, v83
	v_fmamk_f32 v81, v81, 0x3c000000, v154
	v_mul_f32_e32 v82, 0x4b800000, v81
	v_cmp_gt_f32_e32 vcc, s41, v81
	s_nop 1
	v_cndmask_b32_e32 v81, v81, v82, vcc
	v_rsq_f32_e32 v81, v81
	v_lshl_add_u64 v[82:83], v[88:89], 0, v[136:137]
	v_mul_f32_e32 v88, 0x45800000, v81
	v_cndmask_b32_e32 v88, v81, v88, vcc
	v_pk_mul_f32 v[66:67], v[66:67], v[88:89] op_sel_hi:[1,0]
	v_pk_mul_f32 v[64:65], v[64:65], v[88:89] op_sel_hi:[1,0]
	v_pk_mul_f32 v[70:71], v[70:71], v[88:89] op_sel_hi:[1,0]
	v_pk_mul_f32 v[68:69], v[68:69], v[88:89] op_sel_hi:[1,0]
	v_cvt_pk_bf16_f32 v64, v64, v65
	v_cvt_pk_bf16_f32 v65, v66, v67
	v_pk_mul_f32 v[74:75], v[74:75], v[88:89] op_sel_hi:[1,0]
	v_cvt_pk_bf16_f32 v66, v68, v69
	v_cvt_pk_bf16_f32 v67, v70, v71
	v_pk_mul_f32 v[72:73], v[72:73], v[88:89] op_sel_hi:[1,0]
	v_pk_mul_f32 v[78:79], v[78:79], v[88:89] op_sel_hi:[1,0]
	v_pk_mul_f32 v[76:77], v[76:77], v[88:89] op_sel_hi:[1,0]
	global_store_dwordx4 v[82:83], v[64:67], off
	s_nop 1
	v_cvt_pk_bf16_f32 v64, v72, v73
	v_cvt_pk_bf16_f32 v65, v74, v75
	v_cvt_pk_bf16_f32 v66, v76, v77
	v_cvt_pk_bf16_f32 v67, v78, v79
	global_store_dwordx4 v[84:85], v[64:67], off
	s_nop 1
	v_mov_b64_e32 v[68:69], v[194:195]
	v_mov_b64_e32 v[70:71], v[196:197]
	v_mov_b32_e32 v78, v69
	v_mov_b32_e32 v79, v70
	v_mov_b32_e32 v69, v71
	v_pk_add_f32 v[68:69], v[78:79], v[68:69]
	v_mov_b32_e32 v64, s14
	v_add_f32_e32 v68, v68, v69
	v_fmamk_f32 v68, v68, 0x3c000000, v154
	v_add_u32_e32 v66, s4, v145
	v_mul_f32_e32 v69, 0x4b800000, v68
	v_cmp_gt_f32_e32 vcc, s41, v68
	v_bitop3_b32 v76, v155, s43, v64 bitop3:0xc8
	v_or_b32_e32 v64, 16, v80
	v_ashrrev_i32_e32 v67, 31, v66
	v_cndmask_b32_e32 v68, v68, v69, vcc
	v_ashrrev_i32_e32 v65, 31, v64
	v_lshlrev_b64 v[66:67], 12, v[66:67]
	v_rsq_f32_e32 v78, v68
	v_lshl_add_u64 v[72:73], v[64:65], 4, s[44:45]
	v_add_u32_e32 v64, s4, v156
	v_or_b32_e32 v74, v66, v76
	v_ashrrev_i32_e32 v65, 31, v64
	v_mad_u64_u32 v[74:75], s[4:5], v74, s31, v[142:143]
	v_lshlrev_b64 v[64:65], 12, v[64:65]
	v_mad_i32_i24 v75, v67, s31, v75
	v_or_b32_e32 v76, v64, v76
	v_lshl_add_u64 v[68:69], v[74:75], 0, v[136:137]
	v_mul_f32_e32 v74, 0x45800000, v78
	v_mad_u64_u32 v[76:77], s[4:5], v76, s31, v[142:143]
	v_cndmask_b32_e32 v74, v78, v74, vcc
	v_mad_i32_i24 v77, v65, s31, v77
	v_pk_mul_f32 v[50:51], v[50:51], v[74:75] op_sel_hi:[1,0]
	v_pk_mul_f32 v[48:49], v[48:49], v[74:75] op_sel_hi:[1,0]
	v_lshl_add_u64 v[70:71], v[76:77], 0, v[136:137]
	v_pk_mul_f32 v[54:55], v[54:55], v[74:75] op_sel_hi:[1,0]
	v_pk_mul_f32 v[52:53], v[52:53], v[74:75] op_sel_hi:[1,0]
	v_cvt_pk_bf16_f32 v48, v48, v49
	v_cvt_pk_bf16_f32 v49, v50, v51
	v_pk_mul_f32 v[58:59], v[58:59], v[74:75] op_sel_hi:[1,0]
	v_cvt_pk_bf16_f32 v50, v52, v53
	v_cvt_pk_bf16_f32 v51, v54, v55
	v_pk_mul_f32 v[56:57], v[56:57], v[74:75] op_sel_hi:[1,0]
	v_pk_mul_f32 v[62:63], v[62:63], v[74:75] op_sel_hi:[1,0]
	v_pk_mul_f32 v[60:61], v[60:61], v[74:75] op_sel_hi:[1,0]
	global_store_dwordx4 v[68:69], v[48:51], off
	v_or_b32_e32 v52, 32, v80
	v_ashrrev_i32_e32 v53, 31, v52
	v_cvt_pk_bf16_f32 v48, v56, v57
	v_cvt_pk_bf16_f32 v49, v58, v59
	v_cvt_pk_bf16_f32 v50, v60, v61
	v_cvt_pk_bf16_f32 v51, v62, v63
	global_store_dwordx4 v[70:71], v[48:51], off
	s_nop 1
	v_mov_b64_e32 v[48:49], v[198:199]
	v_mov_b64_e32 v[50:51], v[200:201]
	v_bitop3_b32 v56, v80, s8, 16 bitop3:0xc8
	v_or_b32_e32 v54, v66, v56
	v_mad_u64_u32 v[54:55], s[4:5], v54, s31, v[142:143]
	v_mad_i32_i24 v55, v67, s31, v55
	v_or_b32_e32 v56, v64, v56
	v_mad_u64_u32 v[56:57], s[4:5], v56, s31, v[142:143]
	v_mad_i32_i24 v57, v65, s31, v57
	v_lshl_add_u64 v[52:53], v[52:53], 4, s[44:45]
	v_mov_b32_e32 v58, v49
	v_mov_b32_e32 v59, v50
	v_mov_b32_e32 v49, v51
	v_pk_add_f32 v[48:49], v[58:59], v[48:49]
	v_lshl_add_u64 v[50:51], v[56:57], 0, v[136:137]
	v_add_f32_e32 v48, v48, v49
	v_fmamk_f32 v48, v48, 0x3c000000, v154
	v_mul_f32_e32 v49, 0x4b800000, v48
	v_cmp_gt_f32_e32 vcc, s41, v48
	s_nop 1
	v_cndmask_b32_e32 v48, v48, v49, vcc
	v_rsq_f32_e32 v58, v48
	v_lshl_add_u64 v[48:49], v[54:55], 0, v[136:137]
	v_mul_f32_e32 v54, 0x45800000, v58
	v_cndmask_b32_e32 v54, v58, v54, vcc
	v_pk_mul_f32 v[34:35], v[34:35], v[54:55] op_sel_hi:[1,0]
	v_pk_mul_f32 v[32:33], v[32:33], v[54:55] op_sel_hi:[1,0]
	v_pk_mul_f32 v[38:39], v[38:39], v[54:55] op_sel_hi:[1,0]
	v_pk_mul_f32 v[36:37], v[36:37], v[54:55] op_sel_hi:[1,0]
	v_cvt_pk_bf16_f32 v32, v32, v33
	v_cvt_pk_bf16_f32 v33, v34, v35
	v_pk_mul_f32 v[42:43], v[42:43], v[54:55] op_sel_hi:[1,0]
	v_cvt_pk_bf16_f32 v34, v36, v37
	v_cvt_pk_bf16_f32 v35, v38, v39
	v_pk_mul_f32 v[40:41], v[40:41], v[54:55] op_sel_hi:[1,0]
	v_pk_mul_f32 v[46:47], v[46:47], v[54:55] op_sel_hi:[1,0]
	v_pk_mul_f32 v[44:45], v[44:45], v[54:55] op_sel_hi:[1,0]
	global_store_dwordx4 v[48:49], v[32:35], off
	v_or_b32_e32 v36, 48, v80
	v_ashrrev_i32_e32 v37, 31, v36
	v_cvt_pk_bf16_f32 v32, v40, v41
	v_cvt_pk_bf16_f32 v33, v42, v43
	v_cvt_pk_bf16_f32 v34, v44, v45
	v_cvt_pk_bf16_f32 v35, v46, v47
	global_store_dwordx4 v[50:51], v[32:35], off
	s_nop 1
	v_mov_b64_e32 v[32:33], v[202:203]
	v_mov_b64_e32 v[34:35], v[204:205]
	v_bitop3_b32 v40, v80, s9, 32 bitop3:0xc8
	v_or_b32_e32 v38, v66, v40
	v_mad_u64_u32 v[38:39], s[4:5], v38, s31, v[142:143]
	v_mad_i32_i24 v39, v67, s31, v39
	v_or_b32_e32 v40, v64, v40
	v_mad_u64_u32 v[40:41], s[4:5], v40, s31, v[142:143]
	v_mad_i32_i24 v41, v65, s31, v41
	v_lshl_add_u64 v[36:37], v[36:37], 4, s[44:45]
	v_mov_b32_e32 v42, v33
	v_mov_b32_e32 v43, v34
	v_mov_b32_e32 v33, v35
	v_pk_add_f32 v[32:33], v[42:43], v[32:33]
	v_lshl_add_u64 v[34:35], v[40:41], 0, v[136:137]
	v_add_f32_e32 v32, v32, v33
	v_fmamk_f32 v32, v32, 0x3c000000, v154
	v_mul_f32_e32 v33, 0x4b800000, v32
	v_cmp_gt_f32_e32 vcc, s41, v32
	s_nop 1
	v_cndmask_b32_e32 v32, v32, v33, vcc
	v_rsq_f32_e32 v42, v32
	v_lshl_add_u64 v[32:33], v[38:39], 0, v[136:137]
	v_mul_f32_e32 v38, 0x45800000, v42
	v_cndmask_b32_e32 v38, v42, v38, vcc
	v_pk_mul_f32 v[18:19], v[18:19], v[38:39] op_sel_hi:[1,0]
	v_pk_mul_f32 v[16:17], v[16:17], v[38:39] op_sel_hi:[1,0]
	v_pk_mul_f32 v[22:23], v[22:23], v[38:39] op_sel_hi:[1,0]
	v_pk_mul_f32 v[20:21], v[20:21], v[38:39] op_sel_hi:[1,0]
	v_cvt_pk_bf16_f32 v16, v16, v17
	v_cvt_pk_bf16_f32 v17, v18, v19
	v_pk_mul_f32 v[26:27], v[26:27], v[38:39] op_sel_hi:[1,0]
	v_cvt_pk_bf16_f32 v18, v20, v21
	v_cvt_pk_bf16_f32 v19, v22, v23
	v_pk_mul_f32 v[24:25], v[24:25], v[38:39] op_sel_hi:[1,0]
	v_pk_mul_f32 v[30:31], v[30:31], v[38:39] op_sel_hi:[1,0]
	v_pk_mul_f32 v[28:29], v[28:29], v[38:39] op_sel_hi:[1,0]
	global_store_dwordx4 v[32:33], v[16:19], off
	v_bitop3_b32 v22, v80, s53, 48 bitop3:0xc8
	v_or_b32_e32 v20, v66, v22
	v_cvt_pk_bf16_f32 v16, v24, v25
	v_cvt_pk_bf16_f32 v17, v26, v27
	v_cvt_pk_bf16_f32 v18, v28, v29
	v_cvt_pk_bf16_f32 v19, v30, v31
	global_store_dwordx4 v[34:35], v[16:19], off
	s_nop 1
	v_mov_b64_e32 v[16:17], v[206:207]
	v_mov_b64_e32 v[18:19], v[208:209]
	v_or_b32_e32 v24, v64, v22
	v_mad_u64_u32 v[20:21], s[4:5], v20, s31, v[142:143]
	v_mad_i32_i24 v21, v67, s31, v21
	v_mov_b32_e32 v22, v17
	v_mov_b32_e32 v23, v18
	v_mov_b32_e32 v17, v19
	v_pk_add_f32 v[16:17], v[22:23], v[16:17]
	v_lshl_add_u64 v[18:19], v[20:21], 0, v[136:137]
	v_add_f32_e32 v16, v16, v17
	v_fmamk_f32 v16, v16, 0x3c000000, v154
	v_mul_f32_e32 v17, 0x4b800000, v16
	v_cmp_gt_f32_e32 vcc, s41, v16
	s_nop 1
	v_cndmask_b32_e32 v16, v16, v17, vcc
	v_rsq_f32_e32 v22, v16
	v_mad_u64_u32 v[16:17], s[4:5], v24, s31, v[142:143]
	v_mad_i32_i24 v17, v65, s31, v17
	v_mul_f32_e32 v20, 0x45800000, v22
	v_cndmask_b32_e32 v20, v22, v20, vcc
	v_pk_mul_f32 v[2:3], v[2:3], v[20:21] op_sel_hi:[1,0]
	v_pk_mul_f32 v[0:1], v[0:1], v[20:21] op_sel_hi:[1,0]
	v_pk_mul_f32 v[4:5], v[4:5], v[20:21] op_sel_hi:[1,0]
	v_pk_mul_f32 v[6:7], v[6:7], v[20:21] op_sel_hi:[1,0]
	v_cvt_pk_bf16_f32 v0, v0, v1
	v_cvt_pk_bf16_f32 v1, v2, v3
	v_cvt_pk_bf16_f32 v2, v4, v5
	v_lshl_add_u64 v[4:5], v[16:17], 0, v[136:137]
	v_cvt_pk_bf16_f32 v3, v6, v7
	v_pk_mul_f32 v[10:11], v[10:11], v[20:21] op_sel_hi:[1,0]
	v_pk_mul_f32 v[8:9], v[8:9], v[20:21] op_sel_hi:[1,0]
	v_pk_mul_f32 v[14:15], v[14:15], v[20:21] op_sel_hi:[1,0]
	v_pk_mul_f32 v[12:13], v[12:13], v[20:21] op_sel_hi:[1,0]
	global_store_dwordx4 v[18:19], v[0:3], off
	s_and_b64 vcc, exec, s[0:1]
	s_mov_b64 s[0:1], -1
	v_cvt_pk_bf16_f32 v0, v8, v9
	v_cvt_pk_bf16_f32 v1, v10, v11
	v_cvt_pk_bf16_f32 v2, v12, v13
	v_cvt_pk_bf16_f32 v3, v14, v15
	global_store_dwordx4 v[4:5], v[0:3], off
	s_cbranch_vccnz .LBB0_858
	s_andn2_b64 vcc, exec, s[10:11]
	s_cbranch_vccnz .LBB0_857
	s_barrier
	s_branch .LBB0_857
